# adds: ml epilogue reads its 16 per-row denominators with four wide LDS reads instead of 16 serialized ones
# speedup vs baseline: 1.0364x; 1.0011x over previous
.LBB0_197:
	s_or_b64 exec, exec, s[0:1]
	s_add_i32 s0, 16, 0x23a00
	s_waitcnt vmcnt(15)
	v_lshl_add_u32 v10, v95, 4, s0
	s_waitcnt lgkmcnt(0)
	s_barrier
	ds_read_b128 v[136:139], v10
	ds_read_b128 v[140:143], v10 offset:64
	ds_read_b128 v[144:147], v10 offset:128
	ds_read_b128 v[148:151], v10 offset:192
	v_lshlrev_b32_e32 v8, 2, v96
	s_waitcnt vmcnt(14)
	v_mul_u32_u24_e32 v13, 0x410, v95
	v_add_u32_e32 v9, 16, v8
	v_add_lshl_u32 v13, v13, s17, 2
	s_waitcnt lgkmcnt(0)
	v_mul_f32_e32 v12, v24, v136
	v_add_u32_e32 v14, v9, v13
	ds_write_b32 v14, v12 offset:17408
	v_mul_f32_e32 v11, v28, v136
	v_add3_u32 v12, 16, v13, v8
	ds_write_b32 v12, v11 offset:17472
	v_lshl_or_b32 v11, v95, 2, 1
	v_lshl_add_u32 v12, v11, 2, s0
	v_mul_u32_u24_e32 v11, 0x104, v11
	v_add_lshl_u32 v11, v11, s17, 2
	v_add_u32_e32 v9, v9, v11
	v_add3_u32 v8, 16, v11, v8
	v_mul_f32_e32 v13, v25, v137
	ds_write_b32 v9, v13 offset:17408
	v_mul_f32_e32 v9, v29, v137
	ds_write_b32 v8, v9 offset:17472
	v_add_u32_e32 v13, 0x4800, v8
	v_add_u32_e32 v14, 0x4c00, v8
	v_add_u32_e32 v15, 0x8000, v8
	v_add_u32_e32 v12, 0x410, v8
	v_mul_f32_e32 v11, v26, v138
	v_mul_f32_e32 v9, v30, v138
	ds_write2_b32 v13, v11, v9 offset0:4 offset1:20
	v_add_u32_e32 v13, 0x820, v8
	s_movk_i32 s0, 0x410
	v_readlane_b32 s84, v254, 20
	v_readlane_b32 s86, v254, 22
	v_mul_f32_e32 v11, v27, v139
	v_mul_f32_e32 v9, v31, v139
	ds_write2_b32 v14, v11, v9 offset0:8 offset1:24
	v_add_u32_e32 v14, 0x3cf0, v8
	v_readlane_b32 s87, v254, 23
	s_waitcnt vmcnt(11)
	v_lshlrev_b32_e32 v66, 16, v56
	v_and_b32_e32 v65, 0xffff0000, v56
	v_mul_f32_e32 v11, v36, v140
	v_mul_f32_e32 v9, v48, v140
	ds_write2_b32 v15, v11, v9 offset0:60 offset1:76
	v_add_u32_e32 v15, 0x8400, v8
	v_lshlrev_b32_e32 v64, 16, v57
	v_and_b32_e32 v63, 0xffff0000, v57
	v_lshlrev_b32_e32 v57, 16, v58
	v_mul_f32_e32 v11, v37, v141
	v_mul_f32_e32 v9, v49, v141
	ds_write2_b32 v15, v11, v9 offset0:64 offset1:80
	v_add_u32_e32 v15, 0x8800, v8
	v_and_b32_e32 v56, 0xffff0000, v58
	v_readlane_b32 s85, v254, 21
	v_readlane_b32 s88, v254, 24
	v_mul_f32_e32 v11, v38, v142
	v_mul_f32_e32 v9, v50, v142
	ds_write2_b32 v15, v11, v9 offset0:68 offset1:84
	v_add_u32_e32 v15, 0x8c00, v8
	v_readlane_b32 s89, v254, 25
	v_readlane_b32 s90, v254, 26
	v_readlane_b32 s91, v254, 27
	v_mul_f32_e32 v11, v39, v143
	v_mul_f32_e32 v9, v51, v143
	ds_write2_b32 v15, v11, v9 offset0:72 offset1:88
	v_add_u32_e32 v15, 0xc000, v8
	v_readlane_b32 s92, v254, 28
	v_readlane_b32 s93, v254, 29
	v_readlane_b32 s94, v254, 30
	v_mul_f32_e32 v11, v32, v144
	v_mul_f32_e32 v9, v40, v144
	ds_write2_b32 v15, v11, v9 offset0:124 offset1:140
	v_add_u32_e32 v15, 0xc400, v8
	v_readlane_b32 s95, v254, 31
	v_readlane_b32 s96, v254, 32
	v_readlane_b32 s97, v254, 33
	v_mul_f32_e32 v11, v33, v145
	v_mul_f32_e32 v9, v41, v145
	ds_write2_b32 v15, v11, v9 offset0:128 offset1:144
	v_add_u32_e32 v15, 0xc800, v8
	v_add_u32_e32 v8, 0xcc00, v8
	v_readlane_b32 s98, v254, 34
	v_readlane_b32 s99, v254, 35
	v_mul_f32_e32 v11, v34, v146
	v_mul_f32_e32 v9, v42, v146
	ds_write2_b32 v15, v11, v9 offset0:132 offset1:148
	v_mul_f32_e32 v11, v35, v147
	v_mul_f32_e32 v9, v43, v147
	ds_write2_b32 v8, v11, v9 offset0:136 offset1:152
	v_add_u32_e32 v11, 0xfc00, v12
	v_mul_f32_e32 v9, v44, v148
	v_mul_f32_e32 v8, v52, v148
	ds_write2_b32 v11, v9, v8 offset0:184 offset1:200
	v_add_u32_e32 v11, 0xfc00, v13
	v_mul_f32_e32 v9, v45, v149
	v_mul_f32_e32 v8, v53, v149
	ds_write2_b32 v11, v9, v8 offset0:184 offset1:200
	v_add_u32_e32 v11, 0xcc00, v14
	v_lshlrev_b32_e32 v53, 2, v62
	v_mul_f32_e32 v9, v46, v150
	v_mul_f32_e32 v8, v54, v150
	ds_write2_b32 v11, v9, v8 offset0:136 offset1:152
	v_add_u32_e32 v10, 0xd000, v14
	v_and_b32_e32 v54, 0xffff0000, v59
	v_mul_f32_e32 v9, v47, v151
	v_mul_f32_e32 v8, v55, v151
	ds_write2_b32 v10, v9, v8 offset0:140 offset1:156
	v_mul_lo_u32 v8, v94, s0
	v_lshlrev_b32_e32 v9, 2, v104
	v_add3_u32 v10, 16, v8, v9
	s_waitcnt lgkmcnt(0)
	s_barrier
	ds_read_b128 v[40:43], v10 offset:17408
	ds_read_b128 v[36:39], v10 offset:17424
	ds_read_b128 v[32:35], v10 offset:17664
	ds_read_b128 v[28:31], v10 offset:17680
	ds_read_b128 v[24:27], v10 offset:17920
	ds_read_b128 v[20:23], v10 offset:17936
	ds_read_b128 v[12:15], v10 offset:18176
	s_waitcnt lgkmcnt(6)
	v_mul_f32_e32 v11, v41, v41
	v_fmac_f32_e32 v11, v40, v40
	v_fmac_f32_e32 v11, v42, v42
	v_fmac_f32_e32 v11, v43, v43
	s_waitcnt lgkmcnt(5)
	v_fmac_f32_e32 v11, v36, v36
	v_fmac_f32_e32 v11, v37, v37
	v_fmac_f32_e32 v11, v38, v38
	v_fmac_f32_e32 v11, v39, v39
	s_waitcnt lgkmcnt(4)
	v_fmac_f32_e32 v11, v32, v32
	v_fmac_f32_e32 v11, v33, v33
	v_fmac_f32_e32 v11, v34, v34
	v_fmac_f32_e32 v11, v35, v35
	s_waitcnt lgkmcnt(3)
	v_fmac_f32_e32 v11, v28, v28
	v_fmac_f32_e32 v11, v29, v29
	v_fmac_f32_e32 v11, v30, v30
	v_fmac_f32_e32 v11, v31, v31
	s_waitcnt lgkmcnt(2)
	v_fmac_f32_e32 v11, v24, v24
	v_fmac_f32_e32 v11, v25, v25
	v_fmac_f32_e32 v11, v26, v26
	v_fmac_f32_e32 v11, v27, v27
	s_waitcnt lgkmcnt(1)
	v_fmac_f32_e32 v11, v20, v20
	v_fmac_f32_e32 v11, v21, v21
	v_fmac_f32_e32 v11, v22, v22
	v_fmac_f32_e32 v11, v23, v23
	s_waitcnt lgkmcnt(0)
	v_pk_mul_f32 v[8:9], v[12:13], v[12:13]
	v_lshlrev_b32_e32 v55, 16, v59
	v_add_f32_e32 v8, v11, v8
	v_add_f32_e32 v11, v8, v9
	v_pk_mul_f32 v[8:9], v[14:15], v[14:15]
	v_readlane_b32 s0, v251, 57
	v_add_f32_e32 v8, v11, v8
	v_add_f32_e32 v46, v8, v9
	ds_read_b128 v[8:11], v10 offset:18192
	v_readlane_b32 s1, v251, 58
	s_waitcnt lgkmcnt(0)
	v_pk_mul_f32 v[44:45], v[8:9], v[8:9]
	s_nop 0
	v_add_f32_e32 v44, v46, v44
	v_add_f32_e32 v46, v44, v45
	v_pk_mul_f32 v[44:45], v[10:11], v[10:11]
	s_nop 0
	v_add_f32_e32 v44, v46, v44
	v_add_f32_e32 v44, v44, v45
	ds_bpermute_b32 v45, v101, v44
	s_waitcnt lgkmcnt(0)
	v_add_f32_e32 v44, v44, v45
	ds_bpermute_b32 v45, v102, v44
	s_waitcnt lgkmcnt(0)
	v_add_f32_e32 v44, v44, v45
	ds_bpermute_b32 v45, v103, v44
	s_waitcnt lgkmcnt(0)
	v_add_f32_e32 v44, v44, v45
	v_fmamk_f32 v44, v44, 0x3b800000, v182
	v_cmp_gt_f32_e32 vcc, s56, v44
	v_mul_f32_e32 v45, 0x4b800000, v44
	s_nop 0
	v_cndmask_b32_e32 v44, v44, v45, vcc
	v_rsq_f32_e32 v44, v44
	s_nop 0
	v_mul_f32_e32 v45, 0x45800000, v44
	v_cndmask_b32_e32 v52, v44, v45, vcc
	v_mul_f32_e32 v38, v38, v52
	v_mul_f32_e32 v40, v40, v52
	v_mul_f32_e32 v36, v36, v52
	v_mul_f32_e32 v37, v37, v52
	v_mul_f32_e32 v41, v41, v52
	v_mul_f32_e32 v42, v42, v52
	v_mul_f32_e32 v43, v43, v52
	v_mul_f32_e32 v28, v28, v52
	v_mul_f32_e32 v32, v32, v52
	v_mul_f32_e32 v33, v33, v52
	v_mul_f32_e32 v34, v34, v52
	v_mul_f32_e32 v35, v35, v52
	v_mul_f32_e32 v20, v20, v52
	v_mul_f32_e32 v24, v24, v52
	v_mul_f32_e32 v8, v8, v52
	v_mul_f32_e32 v12, v12, v52
	s_waitcnt vmcnt(0)
	v_mul_f32_e32 v38, v206, v38
	v_mul_f32_e32 v40, v208, v40
	v_mul_f32_e32 v36, v204, v36
	v_mul_f32_e32 v37, v205, v37
	v_mul_f32_e32 v44, v38, v55
	v_mul_f32_e32 v38, v39, v52
	v_mul_f32_e32 v40, v40, v66
	v_mul_f32_e32 v41, v209, v41
	v_mul_f32_e32 v36, v36, v57
	v_mul_f32_e32 v37, v37, v56
	v_mul_f32_e32 v38, v207, v38
	v_mul_f32_e32 v41, v41, v65
	v_mul_f32_e32 v45, v38, v54
	v_cvt_pk_bf16_f32 v38, v40, v41
	v_cvt_pk_bf16_f32 v40, v36, v37
	v_lshl_add_u64 v[36:37], s[0:1], 0, v[60:61]
	v_mul_f32_e32 v42, v210, v42
	v_mul_f32_e32 v43, v211, v43
	v_lshl_add_u64 v[36:37], v[36:37], 0, v[156:157]
	v_mul_f32_e32 v42, v42, v64
	v_mul_f32_e32 v43, v43, v63
	v_cvt_pk_bf16_f32 v39, v42, v43
	v_cvt_pk_bf16_f32 v41, v44, v45
	global_store_dwordx4 v[36:37], v[38:41], off
	v_lshlrev_b32_e32 v42, 16, v16
	v_and_b32_e32 v43, 0xffff0000, v16
	v_lshlrev_b32_e32 v44, 16, v17
	v_and_b32_e32 v45, 0xffff0000, v17
	v_lshlrev_b32_e32 v46, 16, v18
	v_and_b32_e32 v47, 0xffff0000, v18
	v_lshlrev_b32_e32 v48, 16, v19
	v_and_b32_e32 v49, 0xffff0000, v19
	v_mul_f32_e32 v16, v28, v212
	v_mul_f32_e32 v28, v16, v46
	v_mul_f32_e32 v16, v29, v52
	v_mul_f32_e32 v16, v16, v213
	v_mul_f32_e32 v29, v16, v47
	v_mul_f32_e32 v16, v30, v52
	v_mul_f32_e32 v16, v16, v214
	v_mul_f32_e32 v30, v16, v48
	v_mul_f32_e32 v16, v31, v52
	v_mul_f32_e32 v16, v16, v215
	v_mul_f32_e32 v32, v32, v216
	v_mul_f32_e32 v33, v33, v217
	v_mul_f32_e32 v34, v34, v218
	v_mul_f32_e32 v35, v35, v219
	v_mul_f32_e32 v19, v16, v49
	v_mul_f32_e32 v32, v32, v42
	v_mul_f32_e32 v33, v33, v43
	v_mul_f32_e32 v34, v34, v44
	v_mul_f32_e32 v35, v35, v45
	v_cvt_pk_bf16_f32 v16, v32, v33
	v_cvt_pk_bf16_f32 v17, v34, v35
	v_cvt_pk_bf16_f32 v18, v28, v29
	v_cvt_pk_bf16_f32 v19, v30, v19
	global_store_dwordx4 v[36:37], v[16:19], off offset:128
	v_lshlrev_b32_e32 v28, 16, v4
	v_and_b32_e32 v29, 0xffff0000, v4
	v_lshlrev_b32_e32 v30, 16, v5
	v_and_b32_e32 v31, 0xffff0000, v5
	v_lshlrev_b32_e32 v32, 16, v6
	v_and_b32_e32 v33, 0xffff0000, v6
	v_lshlrev_b32_e32 v34, 16, v7
	v_and_b32_e32 v35, 0xffff0000, v7
	v_mul_f32_e32 v4, v20, v220
	v_mul_f32_e32 v20, v4, v32
	v_mul_f32_e32 v4, v21, v52
	v_mul_f32_e32 v4, v4, v221
	v_mul_f32_e32 v21, v4, v33
	v_mul_f32_e32 v4, v22, v52
	v_mul_f32_e32 v16, v24, v224
	v_mul_f32_e32 v24, v25, v52
	v_mul_f32_e32 v4, v4, v222
	v_mul_f32_e32 v17, v24, v225
	v_mul_f32_e32 v24, v26, v52
	v_mul_f32_e32 v22, v4, v34
	v_mul_f32_e32 v4, v23, v52
	v_mul_f32_e32 v18, v24, v226
	v_mul_f32_e32 v24, v27, v52
	v_mul_f32_e32 v4, v4, v223
	v_mul_f32_e32 v19, v24, v227
	v_mul_f32_e32 v7, v4, v35
	v_mul_f32_e32 v16, v16, v28
	v_mul_f32_e32 v17, v17, v29
	v_mul_f32_e32 v18, v18, v30
	v_mul_f32_e32 v19, v19, v31
	v_cvt_pk_bf16_f32 v4, v16, v17
	v_cvt_pk_bf16_f32 v5, v18, v19
	v_cvt_pk_bf16_f32 v6, v20, v21
	v_cvt_pk_bf16_f32 v7, v22, v7
	global_store_dwordx4 v[36:37], v[4:7], off offset:256
	v_lshlrev_b32_e32 v16, 16, v0
	v_and_b32_e32 v17, 0xffff0000, v0
	v_lshlrev_b32_e32 v18, 16, v1
	v_and_b32_e32 v19, 0xffff0000, v1
	v_lshlrev_b32_e32 v20, 16, v2
	v_and_b32_e32 v21, 0xffff0000, v2
	v_lshlrev_b32_e32 v22, 16, v3
	v_and_b32_e32 v23, 0xffff0000, v3
	v_mul_f32_e32 v0, v8, v228
	v_mul_f32_e32 v8, v0, v20
	v_mul_f32_e32 v0, v9, v52
	v_mul_f32_e32 v0, v0, v229
	v_mul_f32_e32 v9, v0, v21
	v_mul_f32_e32 v0, v10, v52
	v_mul_f32_e32 v4, v12, v232
	v_mul_f32_e32 v12, v13, v52
	v_mul_f32_e32 v0, v0, v230
	v_mul_f32_e32 v5, v12, v233
	v_mul_f32_e32 v12, v14, v52
	v_mul_f32_e32 v10, v0, v22
	v_mul_f32_e32 v0, v11, v52
	v_mul_f32_e32 v6, v12, v234
	v_mul_f32_e32 v12, v15, v52
	v_mul_f32_e32 v0, v0, v231
	v_mul_f32_e32 v7, v12, v235
	v_mul_f32_e32 v3, v0, v23
	v_mul_f32_e32 v4, v4, v16
	v_mul_f32_e32 v5, v5, v17
	v_mul_f32_e32 v6, v6, v18
	v_mul_f32_e32 v7, v7, v19
	v_cvt_pk_bf16_f32 v0, v4, v5
	v_cvt_pk_bf16_f32 v1, v6, v7
	v_cvt_pk_bf16_f32 v2, v8, v9
	v_cvt_pk_bf16_f32 v3, v10, v3
	global_store_dwordx4 v[36:37], v[0:3], off offset:384
	s_barrier
